# neighbourhood-attention item: query and gate tiles by coalesced LDS-DMA as well (no narrow row-strided loads left in the attention items)
# speedup vs baseline: 1.0198x; 1.0123x over previous
; template <bool NA, bool TRACK>
; DI void attn_item(char* lds, const bf16_t* P, bf16_t* Y, const bf16_t* vt, int rp, int q_off, int k1_off, int nt1,
;                   int vk1, int k2_off, int nt2, int vk2, int g_off, int y_off, int rlo, const float* rpb) {
;     ...
;   if (NA) {
;     rw = rp * 4 + (w >> 1);
;     r0w = clampi(rw - 4, 0, 24);
;     cq = (w & 1) * 32 + r;
;     c0 = clampi(cq - 8, 0, 48);
;     for (int e = tid; e < 15 * 128; e += NTHREADS) {
;       const int dr = e >> 7, dc = (e & 127) - 48;
;       tab[e] = (dc >= 0 && dc < 31) ? rpb[dr * 31 + dc] * LOG2E : 0.f;
;     }
;   }
;   bf16x8 qf[4];
; #pragma unroll
;   for (int ks = 0; ks < 4; ++ks) qf[ks] = *(const bf16x8*)(qp + (size_t)(w * 32 + r) * INW + ks * 16 + h * 8);
;   u32x2 gate[2][4];
; #pragma unroll
;   for (int dm = 0; dm < 2; ++dm)
; #pragma unroll
;     for (int g = 0; g < 4; ++g)
;       gate[dm][g] = *(const u32x2*)(P + g_off + (size_t)(w * 32 + r) * INW + dm * 32 + 8 * g + 4 * h);
; #pragma unroll
;   for (int ks = 0; ks < 4; ++ks) asm volatile("" : "+v"(qf[ks]));
; #pragma unroll
;   for (int dm = 0; dm < 2; ++dm)
; #pragma unroll
;     for (int g = 0; g < 4; ++g) asm volatile("" : "+v"(gate[dm][g]));
;   f32x16 o[2];
;   o[0] = zero16(); o[1] = zero16();
;   f32x16 negm;
; #pragma unroll
;   for (int i = 0; i < 16; ++i) negm[i] = 0.f;
;   float l_run = 0.f;
;   constexpr int TPI = 4;
;   const int niter = (nt + TPI - 1) / TPI;
;   u32x4 rk[TPI], rv[TPI];
;     ...
;   ATT_LOAD(0);
.LBB0_185:
	v_readlane_b32 s2, v255, 10
	v_readlane_b32 s3, v255, 11
	s_nop 3
	s_cmp_eq_u64 s[2:3], 0
	s_cbranch_scc1 .Lna_orig
	v_readlane_b32 s0, v255, 12
	v_readlane_b32 s46, v254, 37
	v_readlane_b32 s47, v254, 38
	s_nop 3
	s_add_i32 s0, s25, s0
	s_mul_i32 s0, s0, 0x744
	s_add_u32 s46, s46, s0
	s_addc_u32 s47, s47, 0
	v_and_b32_e32 v0, 0x7f, v251
	v_subrev_u32_e32 v0, 48, v0
	v_cmp_gt_u32_e32 vcc, 31, v0
	v_med3_i32 v0, v0, 0, 30
	v_lshrrev_b32_e32 v162, 7, v251
	v_mul_u32_u24_e32 v163, 31, v162
	v_add_lshl_u32 v163, v163, v0, 2
	global_load_dword v195, v163, s[46:47]
	global_load_dword v196, v163, s[46:47] offset:496
	global_load_dword v197, v163, s[46:47] offset:992
	v_min_u32_e32 v162, 2, v162
	v_mul_u32_u24_e32 v162, 31, v162
	v_add_lshl_u32 v162, v162, v0, 2
	global_load_dword v198, v162, s[46:47] offset:1488
	v_readlane_b32 s44, v254, 49
	v_readlane_b32 s45, v254, 50
	s_ashr_i32 s13, s12, 31
	s_ashr_i32 s11, s10, 31
	s_mov_b32 s34, s26
	s_ashr_i32 s35, s26, 31
	s_lshl_b64 s[34:35], s[34:35], 1
	s_add_u32 s34, s34, s44
	s_addc_u32 s35, s35, s45
	s_mov_b32 s36, s27
	s_ashr_i32 s37, s27, 31
	s_lshl_b64 s[36:37], s[36:37], 1
	s_add_u32 s36, s36, s44
	s_addc_u32 s37, s37, s45
	s_lshl_b64 s[4:5], s[12:13], 1
	s_add_u32 s4, s4, s44
	s_addc_u32 s5, s5, s45
	s_lshl_b64 s[6:7], s[10:11], 1
	s_add_u32 s6, s6, s44
	s_addc_u32 s7, s7, s45
	s_add_i32 s30, s79, 4
	s_add_i32 s19, s30, 3
	s_lshr_b32 s19, s19, 2
	s_mov_b32 s18, 0
	v_bfe_u32 v183, v251, 5, 1
	v_ashrrev_i32_e32 v0, 1, v251
	s_movk_i32 s0, 0xffe0
	v_bfi_b32 v182, s0, v0, v251
	v_lshlrev_b32_e32 v174, 3, v183
	v_mov_b32_e32 v172, s28
	v_mul_u32_u24_e32 v0, 0x1600, v182
	v_lshl_add_u32 v204, v183, 4, v0
	v_lshl_add_u32 v205, v183, 3, v0
	v_lshrrev_b32_e32 v0, 3, v251
	v_and_b32_e32 v162, 7, v251
	v_mul_u32_u24_e32 v200, 0x1600, v0
	v_lshl_add_u32 v200, v162, 4, v200
	v_mul_u32_u24_e32 v201, 0x1200, v0
	v_lshl_add_u32 v201, v162, 4, v201
	v_bfe_u32 v163, v251, 4, 3
	v_xor_b32_e32 v163, v163, v162
	v_mul_u32_u24_e32 v204, 0x1600, v0
	v_lshl_add_u32 v204, v163, 4, v204
	v_lshrrev_b32_e32 v163, 6, v251
	s_nop 0
	v_readfirstlane_b32 s43, v163
	s_nop 3
	s_lshl_b32 s43, s43, 10
	s_mov_b64 s[14:15], s[34:35]
	s_mov_b64 s[16:17], s[36:37]
	s_add_u32 m0, s43, 0x10000
	s_nop 0
	global_load_lds_dwordx4 v204, s[14:15]
	s_add_u32 m0, s43, 0x18000
	s_nop 0
	global_load_lds_dwordx4 v204, s[16:17]
	s_add_u32 s14, s14, 0x58000
	s_addc_u32 s15, s15, 0
	s_add_u32 s16, s16, 0x58000
	s_addc_u32 s17, s17, 0
	s_add_u32 m0, s43, 0x12000
	s_nop 0
	global_load_lds_dwordx4 v204, s[14:15]
	s_add_u32 m0, s43, 0x1a000
	s_nop 0
	global_load_lds_dwordx4 v204, s[16:17]
	s_add_u32 s14, s14, 0x58000
	s_addc_u32 s15, s15, 0
	s_add_u32 s16, s16, 0x58000
	s_addc_u32 s17, s17, 0
	s_add_u32 m0, s43, 0x14000
	s_nop 0
	global_load_lds_dwordx4 v204, s[14:15]
	s_add_u32 m0, s43, 0x1c000
	s_nop 0
	global_load_lds_dwordx4 v204, s[16:17]
	s_add_u32 s14, s14, 0x58000
	s_addc_u32 s15, s15, 0
	s_add_u32 s16, s16, 0x58000
	s_addc_u32 s17, s17, 0
	s_add_u32 m0, s43, 0x16000
	s_nop 0
	global_load_lds_dwordx4 v204, s[14:15]
	s_add_u32 m0, s43, 0x1e000
	s_nop 0
	global_load_lds_dwordx4 v204, s[16:17]
	s_mov_b32 s31, 0
	s_cmp_lt_i32 s31, s79
	s_cselect_b32 s21, 0, s79
	s_cselect_b32 s22, s4, s6
	s_cselect_b32 s23, s5, s7
	s_cselect_b32 s29, s90, 0x800
	s_sub_i32 s20, s31, s21
	s_mul_i32 s21, s20, 0x58000
	s_add_u32 s14, s22, s21
	s_addc_u32 s15, s23, 0
	s_lshl_b32 s20, s20, 6
	s_add_i32 s20, s20, s29
	s_lshl_b32 s20, s20, 1
	s_add_u32 s16, s8, s20
	s_addc_u32 s17, s9, 0
	global_load_dwordx4 v[130:133], v200, s[14:15]
	global_load_dwordx4 v[134:137], v201, s[16:17]
	s_mov_b32 s31, 1
	s_cmp_lt_i32 s31, s79
	s_cselect_b32 s21, 0, s79
	s_cselect_b32 s22, s4, s6
	s_cselect_b32 s23, s5, s7
	s_cselect_b32 s29, s90, 0x800
	s_sub_i32 s20, s31, s21
	s_mul_i32 s21, s20, 0x58000
	s_add_u32 s14, s22, s21
	s_addc_u32 s15, s23, 0
	s_lshl_b32 s20, s20, 6
	s_add_i32 s20, s20, s29
	s_lshl_b32 s20, s20, 1
	s_add_u32 s16, s8, s20
	s_addc_u32 s17, s9, 0
	global_load_dwordx4 v[138:141], v200, s[14:15]
	global_load_dwordx4 v[142:145], v201, s[16:17]
	s_mov_b32 s31, 2
	s_cmp_lt_i32 s31, s79
	s_cselect_b32 s21, 0, s79
	s_cselect_b32 s22, s4, s6
	s_cselect_b32 s23, s5, s7
	s_cselect_b32 s29, s90, 0x800
	s_sub_i32 s20, s31, s21
	s_mul_i32 s21, s20, 0x58000
	s_add_u32 s14, s22, s21
	s_addc_u32 s15, s23, 0
	s_lshl_b32 s20, s20, 6
	s_add_i32 s20, s20, s29
	s_lshl_b32 s20, s20, 1
	s_add_u32 s16, s8, s20
	s_addc_u32 s17, s9, 0
	global_load_dwordx4 v[146:149], v200, s[14:15]
	global_load_dwordx4 v[150:153], v201, s[16:17]
	s_mov_b32 s31, 3
	s_cmp_lt_i32 s31, s79
	s_cselect_b32 s21, 0, s79
	s_cselect_b32 s22, s4, s6
	s_cselect_b32 s23, s5, s7
	s_cselect_b32 s29, s90, 0x800
	s_sub_i32 s20, s31, s21
	s_mul_i32 s21, s20, 0x58000
	s_add_u32 s14, s22, s21
	s_addc_u32 s15, s23, 0
	s_lshl_b32 s20, s20, 6
	s_add_i32 s20, s20, s29
	s_lshl_b32 s20, s20, 1
	s_add_u32 s16, s8, s20
	s_addc_u32 s17, s9, 0
	global_load_dwordx4 v[154:157], v200, s[14:15]
	global_load_dwordx4 v[158:161], v201, s[16:17]
	s_waitcnt vmcnt(16)
; template <bool NA, bool TRACK>
; DI void attn_item(char* lds, const bf16_t* P, bf16_t* Y, const bf16_t* vt, int rp, int q_off, int k1_off, int nt1,
;                   int vk1, int k2_off, int nt2, int vk2, int g_off, int y_off, int rlo, const float* rpb) {
;     ...
;   if (NA) {
;     rw = rp * 4 + (w >> 1);
;     r0w = clampi(rw - 4, 0, 24);
;     cq = (w & 1) * 32 + r;
;     c0 = clampi(cq - 8, 0, 48);
;     for (int e = tid; e < 15 * 128; e += NTHREADS) {
;       const int dr = e >> 7, dc = (e & 127) - 48;
;       tab[e] = (dc >= 0 && dc < 31) ? rpb[dr * 31 + dc] * LOG2E : 0.f;
;     }
;   }
;   bf16x8 qf[4];
; #pragma unroll
;   for (int ks = 0; ks < 4; ++ks) qf[ks] = *(const bf16x8*)(qp + (size_t)(w * 32 + r) * INW + ks * 16 + h * 8);
;   u32x2 gate[2][4];
; #pragma unroll
;   for (int dm = 0; dm < 2; ++dm)
; #pragma unroll
;     for (int g = 0; g < 4; ++g)
;       gate[dm][g] = *(const u32x2*)(P + g_off + (size_t)(w * 32 + r) * INW + dm * 32 + 8 * g + 4 * h);
; #pragma unroll
;   for (int ks = 0; ks < 4; ++ks) asm volatile("" : "+v"(qf[ks]));
; #pragma unroll
;   for (int dm = 0; dm < 2; ++dm)
; #pragma unroll
;     for (int g = 0; g < 4; ++g) asm volatile("" : "+v"(gate[dm][g]));
;   f32x16 o[2];
;   o[0] = zero16(); o[1] = zero16();
;   f32x16 negm;
; #pragma unroll
;   for (int i = 0; i < 16; ++i) negm[i] = 0.f;
;     ...
;         if (NA) {
;           if (t < nt1) {
;             const float* trow = tab + drow * 128 + 63 - cq;
; #pragma unroll
;             for (int kt = 0; kt < 2; ++kt)
; #pragma unroll
;               for (int i = 0; i < 16; ++i) {
;                 const int kc = kt * 32 + (i & 3) + 8 * (i >> 2) + 4 * h;
;                 const bool ok = (unsigned)(kc - c0) < 16u;
;                 const float t2 = s[kt][i] + trow[kc];
;                 s[kt][i] = ok ? t2 : -1e30f;
;               }
	v_lshlrev_b32_e32 v163, 2, v251
	v_add_u32_e32 v163, 0x20000, v163
	v_mov_b32_e32 v203, 0
	v_mul_f32_e32 v195, 0x3fb8aa3b, v195
	v_cndmask_b32_e32 v195, 0, v195, vcc
	v_max_f32_e64 v203, v203, |v195|
	v_mul_f32_e32 v196, 0x3fb8aa3b, v196
	v_cndmask_b32_e32 v196, 0, v196, vcc
	v_max_f32_e64 v203, v203, |v196|
	v_mul_f32_e32 v197, 0x3fb8aa3b, v197
	v_cndmask_b32_e32 v197, 0, v197, vcc
	v_max_f32_e64 v203, v203, |v197|
	v_mul_f32_e32 v198, 0x3fb8aa3b, v198
	v_cndmask_b32_e32 v198, 0, v198, vcc
	v_max_f32_e64 v203, v203, |v198|
	ds_write_b32 v163, v195
	ds_write_b32 v163, v196 offset:2048
	ds_write_b32 v163, v197 offset:4096
	s_movk_i32 s0, 0x180
	v_cmp_gt_u32_e64 s[2:3], s0, v251
	s_nop 3
	s_and_saveexec_b64 s[14:15], s[2:3]
	ds_write_b32 v163, v198 offset:6144
	s_mov_b64 exec, s[14:15]
	s_mov_b32 s0, 0x41c00000
	v_cmp_lt_f32_e32 vcc, s0, v203
	s_nop 4
	s_cmp_lg_u64 vcc, 0
	s_cselect_b32 s0, 1, 0
	v_mov_b32_e32 v203, s0
	v_lshrrev_b32_e32 v163, 6, v251
	v_lshlrev_b32_e32 v163, 2, v163
	v_add_u32_e32 v163, 0x21e10, v163
	ds_write_b32 v163, v203
	v_lshlrev_b32_e32 v162, 4, v251
	v_xor_b32_e32 v162, v162, v251
	v_and_b32_e32 v162, 0x70, v162
	v_lshl_or_b32 v199, v0, 7, v162
	v_and_b32_e32 v0, 31, v251
	v_lshlrev_b32_e32 v0, 7, v0
	v_bfe_u32 v162, v251, 1, 3
	v_xor_b32_e32 v162, v162, v183
	v_lshl_or_b32 v191, v162, 4, v0
	v_xor_b32_e32 v163, 2, v162
	v_lshl_or_b32 v192, v163, 4, v0
	v_xor_b32_e32 v163, 4, v162
	v_lshl_or_b32 v193, v163, 4, v0
	v_xor_b32_e32 v163, 6, v162
	v_lshl_or_b32 v194, v163, 4, v0
	v_mov_b32_e32 v2, 0
	v_mov_b32_e32 v3, 0
	v_mov_b32_e32 v4, 0
	v_mov_b32_e32 v5, 0
	v_mov_b32_e32 v6, 0
	v_mov_b32_e32 v7, 0
	v_mov_b32_e32 v8, 0
	v_mov_b32_e32 v9, 0
	v_mov_b32_e32 v10, 0
	v_mov_b32_e32 v11, 0
	v_mov_b32_e32 v12, 0
	v_mov_b32_e32 v13, 0
	v_mov_b32_e32 v14, 0
	v_mov_b32_e32 v15, 0
	v_mov_b32_e32 v16, 0
	v_mov_b32_e32 v17, 0
	v_mov_b32_e32 v18, 0
	v_mov_b32_e32 v19, 0
	v_mov_b32_e32 v20, 0
	v_mov_b32_e32 v21, 0
	v_mov_b32_e32 v22, 0
	v_mov_b32_e32 v23, 0
	v_mov_b32_e32 v24, 0
	v_mov_b32_e32 v25, 0
	v_mov_b32_e32 v26, 0
	v_mov_b32_e32 v27, 0
	v_mov_b32_e32 v28, 0
	v_mov_b32_e32 v29, 0
	v_mov_b32_e32 v30, 0
	v_mov_b32_e32 v31, 0
	v_mov_b32_e32 v32, 0
	v_mov_b32_e32 v33, 0
	v_mov_b32_e32 v186, 0
	v_mov_b32_e32 v187, 0
	v_mov_b32_e32 v188, 0
	v_mov_b32_e32 v189, 0
	v_mov_b32_e32 v114, 0
	v_mov_b32_e32 v115, 0
	v_mov_b32_e32 v116, 0
	v_mov_b32_e32 v117, 0
	v_mov_b32_e32 v118, 0
	v_mov_b32_e32 v119, 0
	v_mov_b32_e32 v120, 0
	v_mov_b32_e32 v121, 0
	v_mov_b32_e32 v122, 0
	v_mov_b32_e32 v123, 0
	v_mov_b32_e32 v124, 0
	v_mov_b32_e32 v125, 0
	v_mov_b32_e32 v126, 0
	v_mov_b32_e32 v127, 0
	v_mov_b32_e32 v128, 0
	v_mov_b32_e32 v129, 0
	v_lshrrev_b32_e32 v0, 6, v251
	s_nop 0
	v_readfirstlane_b32 s39, v0
	s_nop 3
	s_lshr_b32 s38, s39, 1
	s_add_i32 s38, s38, s24
	s_sub_i32 s40, s89, s38
	s_add_i32 s40, s40, 7
	s_sub_i32 s38, s38, 4
	s_max_i32 s38, s38, 0
	s_min_i32 s38, s38, 24
	s_sub_i32 s38, s38, s89
	s_and_b32 s39, s39, 1
	v_and_b32_e32 v0, 31, v251
	s_lshl_b32 s0, s39, 5
	v_add_u32_e32 v0, s0, v0
	v_subrev_u32_e32 v162, 8, v0
	v_med3_i32 v162, v162, 0, 48
	v_lshlrev_b32_e32 v163, 2, v183
	v_sub_u32_e32 v162, v163, v162
	v_sub_u32_e32 v0, v163, v0
	v_add_u32_e32 v0, 63, v0
	v_lshlrev_b32_e32 v202, 2, v0
	v_add_u32_e32 v202, 0x20000, v202
	s_cmp_eq_u32 s39, 0
	s_cbranch_scc0 .Lna_mask1
	v_add_u32_e32 v163, 0, v162
	v_cmp_gt_u32_e32 vcc, 16, v163
	s_nop 1
	v_cndmask_b32_e32 v206, v249, v250, vcc
	v_add_u32_e32 v163, 1, v162
	v_cmp_gt_u32_e32 vcc, 16, v163
	s_nop 1
	v_cndmask_b32_e32 v207, v249, v250, vcc
	v_add_u32_e32 v163, 2, v162
	v_cmp_gt_u32_e32 vcc, 16, v163
	s_nop 1
	v_cndmask_b32_e32 v208, v249, v250, vcc
	v_add_u32_e32 v163, 3, v162
	v_cmp_gt_u32_e32 vcc, 16, v163
	s_nop 1
	v_cndmask_b32_e32 v209, v249, v250, vcc
	v_add_u32_e32 v163, 8, v162
	v_cmp_gt_u32_e32 vcc, 16, v163
	s_nop 1
	v_cndmask_b32_e32 v210, v249, v250, vcc
	v_add_u32_e32 v163, 9, v162
	v_cmp_gt_u32_e32 vcc, 16, v163
	s_nop 1
	v_cndmask_b32_e32 v211, v249, v250, vcc
	v_add_u32_e32 v163, 10, v162
	v_cmp_gt_u32_e32 vcc, 16, v163
	s_nop 1
	v_cndmask_b32_e32 v212, v249, v250, vcc
	v_add_u32_e32 v163, 11, v162
	v_cmp_gt_u32_e32 vcc, 16, v163
	s_nop 1
	v_cndmask_b32_e32 v213, v249, v250, vcc
	v_add_u32_e32 v163, 16, v162
	v_cmp_gt_u32_e32 vcc, 16, v163
	s_nop 1
	v_cndmask_b32_e32 v214, v249, v250, vcc
	v_add_u32_e32 v163, 17, v162
	v_cmp_gt_u32_e32 vcc, 16, v163
	s_nop 1
	v_cndmask_b32_e32 v215, v249, v250, vcc
	v_add_u32_e32 v163, 18, v162
	v_cmp_gt_u32_e32 vcc, 16, v163
	s_nop 1
	v_cndmask_b32_e32 v216, v249, v250, vcc
	v_add_u32_e32 v163, 19, v162
	v_cmp_gt_u32_e32 vcc, 16, v163
	s_nop 1
	v_cndmask_b32_e32 v217, v249, v250, vcc
	v_add_u32_e32 v163, 24, v162
	v_cmp_gt_u32_e32 vcc, 16, v163
	s_nop 1
	v_cndmask_b32_e32 v218, v249, v250, vcc
	v_add_u32_e32 v163, 25, v162
	v_cmp_gt_u32_e32 vcc, 16, v163
	s_nop 1
	v_cndmask_b32_e32 v219, v249, v250, vcc
	v_add_u32_e32 v163, 26, v162
	v_cmp_gt_u32_e32 vcc, 16, v163
	s_nop 1
	v_cndmask_b32_e32 v220, v249, v250, vcc
	v_add_u32_e32 v163, 27, v162
	v_cmp_gt_u32_e32 vcc, 16, v163
	s_nop 1
	v_cndmask_b32_e32 v221, v249, v250, vcc
	v_add_u32_e32 v163, 32, v162
	v_cmp_gt_u32_e32 vcc, 16, v163
	s_nop 1
	v_cndmask_b32_e32 v222, v249, v250, vcc
	v_add_u32_e32 v163, 33, v162
	v_cmp_gt_u32_e32 vcc, 16, v163
	s_nop 1
	v_cndmask_b32_e32 v223, v249, v250, vcc
	v_add_u32_e32 v163, 34, v162
	v_cmp_gt_u32_e32 vcc, 16, v163
	s_nop 1
	v_cndmask_b32_e32 v224, v249, v250, vcc
	v_add_u32_e32 v163, 35, v162
	v_cmp_gt_u32_e32 vcc, 16, v163
	s_nop 1
	v_cndmask_b32_e32 v225, v249, v250, vcc
	s_branch .Lna_maskd

; #define ATT_WRITE(IT, HALF) do { _Pragma("unroll") for (int j_ = 0; j_ < TPI; ++j_) { const int t_ = (IT) * TPI + j_; if (t_ < nt) { \
;       char* sl_ = lds + (HALF) * 65536 + j_ * 16384; \
;       *(u32x4*)(sl_ + woff) = rk[j_]; \
;       *(u32x4*)(sl_ + 8192 + woff) = rv[j_]; } } } while (0)
; template <bool NA, bool TRACK>
; DI void attn_item(char* lds, const bf16_t* P, bf16_t* Y, const bf16_t* vt, int rp, int q_off, int k1_off, int nt1,
;                   int vk1, int k2_off, int nt2, int vk2, int g_off, int y_off, int rlo, const float* rpb) {
;     ...
;   bf16x8 qf[4];
; #pragma unroll
;   for (int ks = 0; ks < 4; ++ks) qf[ks] = *(const bf16x8*)(qp + (size_t)(w * 32 + r) * INW + ks * 16 + h * 8);
;   u32x2 gate[2][4];
; #pragma unroll
;   for (int dm = 0; dm < 2; ++dm)
; #pragma unroll
;     for (int g = 0; g < 4; ++g)
;       gate[dm][g] = *(const u32x2*)(P + g_off + (size_t)(w * 32 + r) * INW + dm * 32 + 8 * g + 4 * h);
; #pragma unroll
;   for (int ks = 0; ks < 4; ++ks) asm volatile("" : "+v"(qf[ks]));
; #pragma unroll
;   for (int dm = 0; dm < 2; ++dm)
; #pragma unroll
;     for (int g = 0; g < 4; ++g) asm volatile("" : "+v"(gate[dm][g]));
;   f32x16 o[2];
;   o[0] = zero16(); o[1] = zero16();
;   f32x16 negm;
; #pragma unroll
;   for (int i = 0; i < 16; ++i) negm[i] = 0.f;
;   float l_run = 0.f;
;   constexpr int TPI = 4;
;   const int niter = (nt + TPI - 1) / TPI;
;   u32x4 rk[TPI], rv[TPI];
;     ...
;   ATT_LOAD(0);
;   ATT_WRITE(0, 0);
;   __syncthreads();
.Lna_maskd:
	s_waitcnt vmcnt(0)
	ds_write_b128 v199, v[130:133]
	ds_write_b128 v199, v[134:137] offset:8192
	ds_write_b128 v199, v[138:141] offset:16384
	ds_write_b128 v199, v[142:145] offset:24576
	ds_write_b128 v199, v[146:149] offset:32768
	ds_write_b128 v199, v[150:153] offset:40960
	ds_write_b128 v199, v[154:157] offset:49152
	ds_write_b128 v199, v[158:161] offset:57344
	v_xor_b32_e32 v199, 0x10000, v199
	s_waitcnt lgkmcnt(0)
	s_barrier
	v_and_b32_e32 v0, 31, v251
	v_lshlrev_b32_e32 v0, 7, v0
	v_lshrrev_b32_e32 v162, 6, v251
	v_lshl_or_b32 v0, v162, 12, v0
	v_bfe_u32 v162, v251, 1, 3
	v_xor_b32_e32 v163, v162, v183
	v_or_b32_e32 v204, 0x10000, v0
	v_lshl_or_b32 v205, v163, 4, v204
	ds_read_b128 v[66:69], v205
	v_xor_b32_e32 v205, 2, v163
	v_lshl_or_b32 v205, v205, 4, v204
	ds_read_b128 v[70:73], v205
	v_xor_b32_e32 v205, 4, v163
	v_lshl_or_b32 v205, v205, 4, v204
	ds_read_b128 v[74:77], v205
	v_xor_b32_e32 v205, 6, v163
	v_lshl_or_b32 v205, v205, 4, v204
	ds_read_b128 v[78:81], v205
	v_lshl_or_b32 v0, v183, 3, v0
	v_lshl_or_b32 v0, v162, 4, v0
	v_or_b32_e32 v0, 0x18000, v0
	ds_read_b64 v[184:185], v0
	v_xor_b32_e32 v205, 0x10, v0
	ds_read_b64 v[180:181], v205
	v_xor_b32_e32 v205, 0x20, v0
	ds_read_b64 v[178:179], v205
	v_xor_b32_e32 v205, 0x30, v0
	ds_read_b64 v[176:177], v205
	v_xor_b32_e32 v205, 0x40, v0
	ds_read_b64 v[170:171], v205
	v_xor_b32_e32 v205, 0x50, v0
	ds_read_b64 v[168:169], v205
	v_xor_b32_e32 v205, 0x60, v0
	ds_read_b64 v[166:167], v205
	v_xor_b32_e32 v205, 0x70, v0
	ds_read_b64 v[164:165], v205
	v_mov_b32_e32 v0, 0x21e10
	ds_read_b128 v[130:133], v0
	ds_read_b128 v[134:137], v0 offset:16
	s_waitcnt lgkmcnt(0)
	s_barrier
	v_or3_b32 v130, v130, v131, v132
	v_or3_b32 v134, v134, v135, v136
	v_or3_b32 v130, v130, v133, v137
	v_or_b32_e32 v130, v130, v134
	v_cmp_ne_u32_e32 vcc, 0, v130
	s_nop 3
	s_cmp_lg_u64 vcc, 0
	s_cbranch_scc1 .Lna_orig
